# W2in/W2out weight conversion moved from the prologue phase into the FFN1-in idle slot of the same layer (conv_set masks)
# baseline (speedup 1.0000x reference)
.LBB0_9:
	s_lshl_b32 s2, 1, s28
	s_and_b32 s2, s2, 9
	s_cmp_eq_u32 s2, 0
	s_cbranch_scc1 .LBB0_8
	s_mov_b32 s2, s33
	s_cmp_lt_i32 s28, 2
	s_waitcnt vmcnt(0)
	v_mov_b32_e32 v2, s2
	ds_read2_b32 v[2:3], v2 offset1:1
	s_mov_b64 s[14:15], -1
	s_waitcnt lgkmcnt(0)
	v_readfirstlane_b32 s16, v2
	v_readfirstlane_b32 s17, v3
	s_cbranch_scc1 .LBB0_35
	s_cmp_lt_i32 s28, 3
	s_cbranch_scc1 .LBB0_32
	s_cmp_lg_u32 s28, 3
	s_cbranch_scc0 .LBB0_29
	s_cmp_gt_u32 s28, 7
	s_cbranch_scc0 .LBB0_26
	s_cmp_lt_i32 s28, 9
	s_cbranch_scc1 .LBB0_23
	s_cmp_lt_i32 s28, 10
	s_mov_b64 s[12:13], -1
	s_cbranch_scc1 .LBB0_21
	s_cmp_lg_u32 s28, 10
	s_mov_b64 s[10:11], -1
	s_cbranch_scc0 .LBB0_18
	v_readlane_b32 s2, v254, 0
	s_add_i32 s6, s28, -11
	s_mov_b64 s[10:11], 0
	v_mov_b32_e32 v2, s2
	ds_read2_b32 v[2:3], v2 offset1:1
	s_lshl_b64 s[2:3], s[6:7], 21
	s_waitcnt lgkmcnt(0)
	v_readfirstlane_b32 s8, v2
	v_readfirstlane_b32 s9, v3
	s_add_u32 s8, s8, s2
	s_addc_u32 s9, s9, s3
	s_lshl_b64 s[2:3], s[6:7], 20
	s_add_u32 s2, s16, s2
	s_addc_u32 s3, s17, s3
	s_add_u32 s2, s2, 0x3380000
	s_addc_u32 s3, s3, 0

.LBB0_169:
	s_lshl_b32 s2, 1, s28
	s_and_b32 s2, s2, 0
	s_cmp_eq_u32 s2, 0
	s_cbranch_scc1 .LBB0_168
	s_mov_b32 s2, s33
	s_cmp_lt_i32 s28, 2
	s_waitcnt vmcnt(0)
	v_mov_b32_e32 v2, s2
	ds_read2_b32 v[2:3], v2 offset1:1
	s_mov_b64 s[14:15], -1
	s_waitcnt lgkmcnt(0)
	v_readfirstlane_b32 s16, v2
	v_readfirstlane_b32 s17, v3
	s_cbranch_scc1 .LBB0_195
	s_cmp_lt_i32 s28, 3
	s_cbranch_scc1 .LBB0_192
	s_cmp_lg_u32 s28, 3
	s_cbranch_scc0 .LBB0_189
	s_cmp_gt_u32 s28, 7
	s_cbranch_scc0 .LBB0_186
	s_cmp_lt_i32 s28, 9
	s_cbranch_scc1 .LBB0_183
	s_cmp_lt_i32 s28, 10
	s_mov_b64 s[12:13], -1
	s_cbranch_scc1 .LBB0_181
	s_cmp_lg_u32 s28, 10
	s_mov_b64 s[10:11], -1
	s_cbranch_scc0 .LBB0_178
	v_readlane_b32 s2, v254, 0
	s_add_i32 s6, s28, -11
	s_mov_b64 s[10:11], 0
	v_mov_b32_e32 v2, s2
	ds_read2_b32 v[2:3], v2 offset1:1
	s_lshl_b64 s[2:3], s[6:7], 21
	s_waitcnt lgkmcnt(0)
	v_readfirstlane_b32 s8, v2
	v_readfirstlane_b32 s9, v3
	s_add_u32 s2, s8, s2
	s_addc_u32 s3, s9, s3
	s_add_u32 s8, s2, 0x400000
	s_addc_u32 s9, s3, 0
	s_lshl_b64 s[2:3], s[6:7], 20
	s_add_u32 s2, s16, s2
	s_addc_u32 s3, s17, s3
	s_add_u32 s2, s2, 0x6800000
	s_addc_u32 s3, s3, 0

.LBB0_414:
	s_lshl_b32 s0, 1, s24
	s_and_b32 s0, s0, 0x606
	s_cmp_eq_u32 s0, 0
	s_cbranch_scc1 .LBB0_413
	s_mov_b32 s0, s33
	s_mov_b64 s[16:17], -1
	v_mov_b32_e32 v0, s0
	ds_read2_b32 v[2:3], v0 offset1:1
	s_waitcnt lgkmcnt(0)
	v_readfirstlane_b32 s0, v2
	v_readfirstlane_b32 s1, v3
	s_add_u32 s0, s0, s54
	s_addc_u32 s1, s1, 0
	s_add_u32 s14, s0, 0x100000
	s_addc_u32 s15, s1, 0
	s_cmp_lt_i32 s24, 2
	s_cbranch_scc1 .LBB0_440
	s_cmp_lt_i32 s24, 3
	s_cbranch_scc1 .LBB0_437
	s_cmp_lg_u32 s24, 3
	s_cbranch_scc0 .LBB0_434
	s_cmp_gt_u32 s24, 7
	s_cbranch_scc0 .LBB0_431
	s_cmp_lt_i32 s24, 9
	s_cbranch_scc1 .LBB0_428
	s_cmp_lt_i32 s24, 10
	s_mov_b64 s[10:11], -1
	s_cbranch_scc1 .LBB0_426
	s_cmp_lg_u32 s24, 10
	s_mov_b64 s[8:9], -1
	s_cbranch_scc0 .LBB0_423
	v_readlane_b32 s0, v254, 0
	s_add_i32 s94, s24, -11
	s_mov_b64 s[8:9], 0
	v_mov_b32_e32 v0, s0
	ds_read2_b32 v[2:3], v0 offset1:1
	s_waitcnt lgkmcnt(0)
	v_readfirstlane_b32 s0, v2
	v_readfirstlane_b32 s1, v3
	s_add_u32 s6, s0, s4
	s_addc_u32 s7, s1, s5
	s_lshl_b64 s[0:1], s[94:95], 21
	s_add_u32 s6, s6, s0
	s_addc_u32 s7, s7, s1
	s_lshl_b64 s[0:1], s[94:95], 20
	s_add_u32 s0, s14, s0
	s_addc_u32 s1, s15, s1
	s_add_u32 s0, s0, 0x3280000
	s_addc_u32 s1, s1, 0
